# Gray MFMA order; K-loop s_setprio flips and the redundant lgkmcnt(0) after the pre-MFMA barrier removed (MFMA issues right after barrier release)
# speedup vs baseline: 1.0128x; 1.0058x over previous
; #define PG8_STAGE(bufoff, gbase, voff) do { _Pragma("unroll") for (int _i = 0; _i < 2; ++_i) \
;         __builtin_amdgcn_global_load_lds((const unsigned*)((const char*)(gbase) + (voff)[_i]), (PG8_LAS unsigned*)(lds + (bufoff) + ldsw + _i * 8192), 16, 0, 0); } while (0)
; #define PG8_LDA(dst, b, h) do { _Pragma("unroll") for (int m = 0; m < 4; ++m) _Pragma("unroll") for (int k = 0; k < 2; ++k) dst[m][k] = *(const PG8_LAS bf16x8*)(lds + PG8_SA(b, h) + aoff + m * 2048 + k * 1024); } while (0)
; #define PG8_LDB(dst, b, h) do { _Pragma("unroll") for (int n = 0; n < 2; ++n) _Pragma("unroll") for (int k = 0; k < 2; ++k) dst[n][k] = *(const PG8_LAS bf16x8*)(lds + PG8_SB(b, h) + boff + n * 2048 + k * 1024); } while (0)
; #define PG8_MMA(ai, bj, At, Bt) do { __builtin_amdgcn_s_setprio(1); _Pragma("unroll") for (int m = 0; m < 4; ++m) _Pragma("unroll") for (int n = 0; n < 2; ++n) _Pragma("unroll") for (int k = 0; k < 2; ++k) \
;         acc[ai][bj][m][n] = __builtin_amdgcn_mfma_f32_16x16x32_bf16(Bt[n][k], At[m][k], acc[ai][bj][m][n], 0, 0, 0); __builtin_amdgcn_s_setprio(0); } while (0)
; #define PG8_WAIT_V(n) asm volatile("s_waitcnt vmcnt(" #n ")" ::: "memory")
; #define PG8_WAIT_L(n) asm volatile("s_waitcnt lgkmcnt(" #n ")" ::: "memory")
; #define PG8_BAR __builtin_amdgcn_s_barrier()
; #define PG8_SCHED __builtin_amdgcn_sched_barrier(0)
; template <class Epi, class Sched, bool ALIGN_EPI = false, bool SP2 = false>
; __device__ __forceinline__ void gemm_phase(PG8_LAS unsigned char* lds, const Gemm g, const Sched& S, const Epi& E) {
;     ...
;             PG8_LDB(B0, 0, 0); PG8_LDB(B1, 0, 1); PG8_SCHED; PG8_LDA(At, 0, 0); PG8_STAGE(PG8_SA(1, 1), a1 + hstep, voffA);
;             PG8_WAIT_V(8); PG8_WAIT_L(0); PG8_BAR; PG8_MMA(0, 0, At, B0); PG8_MMA(0, 1, At, B1); PG8_BAR; PG8_SCHED;
;             PG8_LDA(At, 0, 1); PG8_STAGE(PG8_SB(0, 0), b2, voffB); PG8_STAGE(PG8_SB(0, 1), b2 + hstep, voffB); PG8_STAGE(PG8_SA(0, 0), a2, voffA);
;             PG8_WAIT_V(8); PG8_WAIT_L(0); PG8_BAR; PG8_MMA(1, 0, At, B0); PG8_MMA(1, 1, At, B1); PG8_BAR; PG8_SCHED;
.LBB0_238:
	s_add_u32 s2, s24, 0x8000
	s_addc_u32 s3, s25, 0
	s_cmp_eq_u32 s71, 12
	s_cselect_b32 s46, s67, s2
	s_cselect_b32 s47, s11, s3
	s_cselect_b32 s42, s68, s69
	s_cselect_b32 s43, s9, s70
	s_add_u32 s26, s46, 0x4000
	s_addc_u32 s27, s47, 0
	v_add_u32_e32 v148, s76, v150
	s_add_i32 s72, 0, 0x14000
	ds_read_b128 v[144:147], v148
	ds_read_b128 v[160:163], v148 offset:1024
	ds_read_b128 v[164:167], v148 offset:2048
	ds_read_b128 v[168:171], v148 offset:3072
	v_add_u32_e32 v148, s72, v150
	ds_read_b128 v[172:175], v148
	ds_read_b128 v[176:179], v148 offset:1024
	ds_read_b128 v[180:183], v148 offset:2048
	ds_read_b128 v[184:187], v148 offset:3072
	v_lshl_add_u64 v[148:149], s[24:25], 0, v[142:143]
	s_add_i32 m0, s23, 0xc000
	ds_read_b128 v[188:191], v152
	ds_read_b128 v[206:209], v152 offset:1024
	ds_read_b128 v[210:213], v152 offset:2048
	ds_read_b128 v[214:217], v152 offset:3072
	ds_read_b128 v[218:221], v152 offset:4096
	ds_read_b128 v[222:225], v152 offset:5120
	ds_read_b128 v[226:229], v152 offset:6144
	ds_read_b128 v[230:233], v152 offset:7168
	global_load_lds_dwordx4 v[148:149], off
	v_lshl_add_u64 v[148:149], s[24:25], 0, v[140:141]
	s_add_i32 m0, s23, 0xe000
	s_nop 0
	global_load_lds_dwordx4 v[148:149], off
	s_waitcnt vmcnt(8)
	s_waitcnt lgkmcnt(0)
	s_barrier
	v_mfma_f32_16x16x32_bf16 v[126:129], v[144:147], v[188:191], v[126:129]
	v_mfma_f32_16x16x32_bf16 v[126:129], v[160:163], v[206:209], v[126:129]
	v_mfma_f32_16x16x32_bf16 v[122:125], v[168:171], v[206:209], v[122:125]
	v_mfma_f32_16x16x32_bf16 v[122:125], v[164:167], v[188:191], v[122:125]
	v_mfma_f32_16x16x32_bf16 v[106:109], v[164:167], v[210:213], v[106:109]
	v_mfma_f32_16x16x32_bf16 v[106:109], v[168:171], v[214:217], v[106:109]
	v_mfma_f32_16x16x32_bf16 v[110:113], v[160:163], v[214:217], v[110:113]
	v_mfma_f32_16x16x32_bf16 v[110:113], v[144:147], v[210:213], v[110:113]
	v_mfma_f32_16x16x32_bf16 v[94:97], v[144:147], v[218:221], v[94:97]
	v_mfma_f32_16x16x32_bf16 v[94:97], v[160:163], v[222:225], v[94:97]
	v_mfma_f32_16x16x32_bf16 v[90:93], v[168:171], v[222:225], v[90:93]
	v_mfma_f32_16x16x32_bf16 v[90:93], v[164:167], v[218:221], v[90:93]
	v_mfma_f32_16x16x32_bf16 v[74:77], v[164:167], v[226:229], v[74:77]
	v_mfma_f32_16x16x32_bf16 v[74:77], v[168:171], v[230:233], v[74:77]
	v_mfma_f32_16x16x32_bf16 v[78:81], v[160:163], v[230:233], v[78:81]
	v_mfma_f32_16x16x32_bf16 v[78:81], v[144:147], v[226:229], v[78:81]
	v_mfma_f32_16x16x32_bf16 v[118:121], v[172:175], v[188:191], v[118:121]
	v_mfma_f32_16x16x32_bf16 v[118:121], v[176:179], v[206:209], v[118:121]
	v_mfma_f32_16x16x32_bf16 v[114:117], v[184:187], v[206:209], v[114:117]
	v_mfma_f32_16x16x32_bf16 v[114:117], v[180:183], v[188:191], v[114:117]
	v_mfma_f32_16x16x32_bf16 v[98:101], v[180:183], v[210:213], v[98:101]
	v_mfma_f32_16x16x32_bf16 v[98:101], v[184:187], v[214:217], v[98:101]
	v_mfma_f32_16x16x32_bf16 v[102:105], v[176:179], v[214:217], v[102:105]
	v_mfma_f32_16x16x32_bf16 v[102:105], v[172:175], v[210:213], v[102:105]
	v_mfma_f32_16x16x32_bf16 v[86:89], v[172:175], v[218:221], v[86:89]
	v_mfma_f32_16x16x32_bf16 v[86:89], v[176:179], v[222:225], v[86:89]
	v_mfma_f32_16x16x32_bf16 v[82:85], v[184:187], v[222:225], v[82:85]
	v_mfma_f32_16x16x32_bf16 v[82:85], v[180:183], v[218:221], v[82:85]
	v_mfma_f32_16x16x32_bf16 v[66:69], v[180:183], v[226:229], v[66:69]
	v_mfma_f32_16x16x32_bf16 v[66:69], v[184:187], v[230:233], v[66:69]
	v_mfma_f32_16x16x32_bf16 v[70:73], v[176:179], v[230:233], v[70:73]
	v_mfma_f32_16x16x32_bf16 v[70:73], v[172:175], v[226:229], v[70:73]
	s_barrier
	s_add_i32 s24, s76, s51
	v_lshl_add_u64 v[148:149], s[42:43], 0, v[132:133]
	s_mov_b32 m0, s24
	ds_read_b128 v[188:191], v152 offset:16384
	ds_read_b128 v[206:209], v152 offset:17408
	ds_read_b128 v[210:213], v152 offset:18432
	ds_read_b128 v[214:217], v152 offset:19456
	ds_read_b128 v[218:221], v152 offset:20480
	ds_read_b128 v[222:225], v152 offset:21504
	ds_read_b128 v[226:229], v152 offset:22528
	ds_read_b128 v[230:233], v152 offset:23552
	global_load_lds_dwordx4 v[148:149], off
	s_add_i32 m0, s24, 0x2000
	s_add_u32 s24, s42, 0x40000
	v_lshl_add_u64 v[234:235], s[42:43], 0, v[136:137]
	s_addc_u32 s25, s43, 0
	s_add_i32 s72, s72, s51
	global_load_lds_dwordx4 v[234:235], off
	v_lshl_add_u64 v[236:237], s[24:25], 0, v[132:133]
	s_mov_b32 m0, s72
	s_nop 0
	global_load_lds_dwordx4 v[236:237], off
	v_lshl_add_u64 v[236:237], s[24:25], 0, v[136:137]
	s_add_i32 m0, s72, 0x2000
	s_nop 0
	global_load_lds_dwordx4 v[236:237], off
	v_lshl_add_u64 v[236:237], s[46:47], 0, v[130:131]
	s_mov_b32 m0, s23
	s_nop 0
	global_load_lds_dwordx4 v[236:237], off
	v_lshl_add_u64 v[236:237], s[46:47], 0, v[134:135]
	s_mov_b32 m0, s56
	s_nop 0
	global_load_lds_dwordx4 v[236:237], off
	s_waitcnt vmcnt(8)
	s_waitcnt lgkmcnt(0)
	s_barrier
; #define PG8_STAGE(bufoff, gbase, voff) do { _Pragma("unroll") for (int _i = 0; _i < 2; ++_i) \
;         __builtin_amdgcn_global_load_lds((const unsigned*)((const char*)(gbase) + (voff)[_i]), (PG8_LAS unsigned*)(lds + (bufoff) + ldsw + _i * 8192), 16, 0, 0); } while (0)
; #define PG8_LDA(dst, b, h) do { _Pragma("unroll") for (int m = 0; m < 4; ++m) _Pragma("unroll") for (int k = 0; k < 2; ++k) dst[m][k] = *(const PG8_LAS bf16x8*)(lds + PG8_SA(b, h) + aoff + m * 2048 + k * 1024); } while (0)
; #define PG8_LDB(dst, b, h) do { _Pragma("unroll") for (int n = 0; n < 2; ++n) _Pragma("unroll") for (int k = 0; k < 2; ++k) dst[n][k] = *(const PG8_LAS bf16x8*)(lds + PG8_SB(b, h) + boff + n * 2048 + k * 1024); } while (0)
; #define PG8_MMA(ai, bj, At, Bt) do { __builtin_amdgcn_s_setprio(1); _Pragma("unroll") for (int m = 0; m < 4; ++m) _Pragma("unroll") for (int n = 0; n < 2; ++n) _Pragma("unroll") for (int k = 0; k < 2; ++k) \
;         acc[ai][bj][m][n] = __builtin_amdgcn_mfma_f32_16x16x32_bf16(Bt[n][k], At[m][k], acc[ai][bj][m][n], 0, 0, 0); __builtin_amdgcn_s_setprio(0); } while (0)
; #define PG8_WAIT_V(n) asm volatile("s_waitcnt vmcnt(" #n ")" ::: "memory")
; #define PG8_WAIT_L(n) asm volatile("s_waitcnt lgkmcnt(" #n ")" ::: "memory")
; #define PG8_BAR __builtin_amdgcn_s_barrier()
; #define PG8_SCHED __builtin_amdgcn_sched_barrier(0)
; template <class Epi, class Sched, bool ALIGN_EPI = false, bool SP2 = false>
; __device__ __forceinline__ void gemm_phase(PG8_LAS unsigned char* lds, const Gemm g, const Sched& S, const Epi& E) {
;     ...
;             PG8_WAIT_V(8); PG8_WAIT_L(0); PG8_BAR; PG8_MMA(1, 0, At, B0); PG8_MMA(1, 1, At, B1); PG8_BAR; PG8_SCHED;
;             PG8_LDB(B0, 1, 0); PG8_LDB(B1, 1, 1); PG8_SCHED; PG8_LDA(At, 1, 0); PG8_STAGE(PG8_SA(0, 1), a2 + hstep, voffA);
;             PG8_WAIT_V(8); PG8_WAIT_L(0); PG8_BAR; PG8_MMA(0, 0, At, B0); PG8_MMA(0, 1, At, B1); PG8_BAR; PG8_SCHED;
	v_mfma_f32_16x16x32_bf16 v[62:65], v[144:147], v[188:191], v[62:65]
	v_mfma_f32_16x16x32_bf16 v[62:65], v[160:163], v[206:209], v[62:65]
	v_mfma_f32_16x16x32_bf16 v[58:61], v[168:171], v[206:209], v[58:61]
	v_mfma_f32_16x16x32_bf16 v[58:61], v[164:167], v[188:191], v[58:61]
	v_mfma_f32_16x16x32_bf16 v[42:45], v[164:167], v[210:213], v[42:45]
	v_mfma_f32_16x16x32_bf16 v[42:45], v[168:171], v[214:217], v[42:45]
	v_mfma_f32_16x16x32_bf16 v[46:49], v[160:163], v[214:217], v[46:49]
	v_mfma_f32_16x16x32_bf16 v[46:49], v[144:147], v[210:213], v[46:49]
	v_mfma_f32_16x16x32_bf16 v[30:33], v[144:147], v[218:221], v[30:33]
	v_mfma_f32_16x16x32_bf16 v[30:33], v[160:163], v[222:225], v[30:33]
	v_mfma_f32_16x16x32_bf16 v[26:29], v[168:171], v[222:225], v[26:29]
	v_mfma_f32_16x16x32_bf16 v[26:29], v[164:167], v[218:221], v[26:29]
	v_mfma_f32_16x16x32_bf16 v[10:13], v[164:167], v[226:229], v[10:13]
	v_mfma_f32_16x16x32_bf16 v[10:13], v[168:171], v[230:233], v[10:13]
	v_mfma_f32_16x16x32_bf16 v[14:17], v[160:163], v[230:233], v[14:17]
	v_mfma_f32_16x16x32_bf16 v[14:17], v[144:147], v[226:229], v[14:17]
	v_mfma_f32_16x16x32_bf16 v[54:57], v[172:175], v[188:191], v[54:57]
	v_mfma_f32_16x16x32_bf16 v[54:57], v[176:179], v[206:209], v[54:57]
	v_mfma_f32_16x16x32_bf16 v[50:53], v[184:187], v[206:209], v[50:53]
	v_mfma_f32_16x16x32_bf16 v[50:53], v[180:183], v[188:191], v[50:53]
	v_mfma_f32_16x16x32_bf16 v[34:37], v[180:183], v[210:213], v[34:37]
	v_mfma_f32_16x16x32_bf16 v[34:37], v[184:187], v[214:217], v[34:37]
	v_mfma_f32_16x16x32_bf16 v[38:41], v[176:179], v[214:217], v[38:41]
	v_mfma_f32_16x16x32_bf16 v[38:41], v[172:175], v[210:213], v[38:41]
	v_mfma_f32_16x16x32_bf16 v[22:25], v[172:175], v[218:221], v[22:25]
	v_mfma_f32_16x16x32_bf16 v[22:25], v[176:179], v[222:225], v[22:25]
	v_mfma_f32_16x16x32_bf16 v[18:21], v[184:187], v[222:225], v[18:21]
	v_mfma_f32_16x16x32_bf16 v[18:21], v[180:183], v[218:221], v[18:21]
	v_mfma_f32_16x16x32_bf16 v[2:5], v[180:183], v[226:229], v[2:5]
	v_mfma_f32_16x16x32_bf16 v[2:5], v[184:187], v[230:233], v[2:5]
	v_mfma_f32_16x16x32_bf16 v[6:9], v[176:179], v[230:233], v[6:9]
	v_mfma_f32_16x16x32_bf16 v[6:9], v[172:175], v[226:229], v[6:9]
	s_barrier
	s_add_i32 s72, 0, 0x18000
	v_add_u32_e32 v153, s72, v150
	s_add_i32 s73, 0, 0x1c000
	ds_read_b128 v[144:147], v153
	ds_read_b128 v[160:163], v153 offset:1024
	ds_read_b128 v[164:167], v153 offset:2048
	ds_read_b128 v[168:171], v153 offset:3072
	v_add_u32_e32 v153, s73, v150
	ds_read_b128 v[172:175], v153
	ds_read_b128 v[176:179], v153 offset:1024
	ds_read_b128 v[180:183], v153 offset:2048
	ds_read_b128 v[184:187], v153 offset:3072
	s_add_u32 s24, s46, 0x40000
	s_addc_u32 s25, s47, 0
	s_mov_b32 m0, s57
	v_lshl_add_u64 v[236:237], s[24:25], 0, v[130:131]
	ds_read_b128 v[188:191], v152 offset:32768
	ds_read_b128 v[206:209], v152 offset:33792
	ds_read_b128 v[210:213], v152 offset:34816
	ds_read_b128 v[214:217], v152 offset:35840
	ds_read_b128 v[218:221], v152 offset:36864
	ds_read_b128 v[222:225], v152 offset:37888
	ds_read_b128 v[226:229], v152 offset:38912
	ds_read_b128 v[230:233], v152 offset:39936
	global_load_lds_dwordx4 v[236:237], off
	v_lshl_add_u64 v[236:237], s[24:25], 0, v[134:135]
	s_mov_b32 m0, s58
	s_nop 0
	global_load_lds_dwordx4 v[236:237], off
	s_waitcnt vmcnt(8)
	s_waitcnt lgkmcnt(0)
	s_barrier
	v_mfma_f32_16x16x32_bf16 v[126:129], v[144:147], v[188:191], v[126:129]
	v_mfma_f32_16x16x32_bf16 v[126:129], v[160:163], v[206:209], v[126:129]
	v_mfma_f32_16x16x32_bf16 v[122:125], v[168:171], v[206:209], v[122:125]
	v_mfma_f32_16x16x32_bf16 v[122:125], v[164:167], v[188:191], v[122:125]
	v_mfma_f32_16x16x32_bf16 v[106:109], v[164:167], v[210:213], v[106:109]
	v_mfma_f32_16x16x32_bf16 v[106:109], v[168:171], v[214:217], v[106:109]
	v_mfma_f32_16x16x32_bf16 v[110:113], v[160:163], v[214:217], v[110:113]
	v_mfma_f32_16x16x32_bf16 v[110:113], v[144:147], v[210:213], v[110:113]
	v_mfma_f32_16x16x32_bf16 v[94:97], v[144:147], v[218:221], v[94:97]
	v_mfma_f32_16x16x32_bf16 v[94:97], v[160:163], v[222:225], v[94:97]
	v_mfma_f32_16x16x32_bf16 v[90:93], v[168:171], v[222:225], v[90:93]
	v_mfma_f32_16x16x32_bf16 v[90:93], v[164:167], v[218:221], v[90:93]
	v_mfma_f32_16x16x32_bf16 v[74:77], v[164:167], v[226:229], v[74:77]
	v_mfma_f32_16x16x32_bf16 v[74:77], v[168:171], v[230:233], v[74:77]
	v_mfma_f32_16x16x32_bf16 v[78:81], v[160:163], v[230:233], v[78:81]
	v_mfma_f32_16x16x32_bf16 v[78:81], v[144:147], v[226:229], v[78:81]
	v_mfma_f32_16x16x32_bf16 v[118:121], v[172:175], v[188:191], v[118:121]
	v_mfma_f32_16x16x32_bf16 v[118:121], v[176:179], v[206:209], v[118:121]
	v_mfma_f32_16x16x32_bf16 v[114:117], v[184:187], v[206:209], v[114:117]
	v_mfma_f32_16x16x32_bf16 v[114:117], v[180:183], v[188:191], v[114:117]
	v_mfma_f32_16x16x32_bf16 v[98:101], v[180:183], v[210:213], v[98:101]
	v_mfma_f32_16x16x32_bf16 v[98:101], v[184:187], v[214:217], v[98:101]
	v_mfma_f32_16x16x32_bf16 v[102:105], v[176:179], v[214:217], v[102:105]
	v_mfma_f32_16x16x32_bf16 v[102:105], v[172:175], v[210:213], v[102:105]
	v_mfma_f32_16x16x32_bf16 v[86:89], v[172:175], v[218:221], v[86:89]
	v_mfma_f32_16x16x32_bf16 v[86:89], v[176:179], v[222:225], v[86:89]
	v_mfma_f32_16x16x32_bf16 v[82:85], v[184:187], v[222:225], v[82:85]
	v_mfma_f32_16x16x32_bf16 v[82:85], v[180:183], v[218:221], v[82:85]
	v_mfma_f32_16x16x32_bf16 v[66:69], v[180:183], v[226:229], v[66:69]
	v_mfma_f32_16x16x32_bf16 v[66:69], v[184:187], v[230:233], v[66:69]
	v_mfma_f32_16x16x32_bf16 v[70:73], v[176:179], v[230:233], v[70:73]
	v_mfma_f32_16x16x32_bf16 v[70:73], v[172:175], v[226:229], v[70:73]
	s_barrier
; #define PG8_STAGE(bufoff, gbase, voff) do { _Pragma("unroll") for (int _i = 0; _i < 2; ++_i) \
;         __builtin_amdgcn_global_load_lds((const unsigned*)((const char*)(gbase) + (voff)[_i]), (PG8_LAS unsigned*)(lds + (bufoff) + ldsw + _i * 8192), 16, 0, 0); } while (0)
; #define PG8_LDA(dst, b, h) do { _Pragma("unroll") for (int m = 0; m < 4; ++m) _Pragma("unroll") for (int k = 0; k < 2; ++k) dst[m][k] = *(const PG8_LAS bf16x8*)(lds + PG8_SA(b, h) + aoff + m * 2048 + k * 1024); } while (0)
; #define PG8_MMA(ai, bj, At, Bt) do { __builtin_amdgcn_s_setprio(1); _Pragma("unroll") for (int m = 0; m < 4; ++m) _Pragma("unroll") for (int n = 0; n < 2; ++n) _Pragma("unroll") for (int k = 0; k < 2; ++k) \
;         acc[ai][bj][m][n] = __builtin_amdgcn_mfma_f32_16x16x32_bf16(Bt[n][k], At[m][k], acc[ai][bj][m][n], 0, 0, 0); __builtin_amdgcn_s_setprio(0); } while (0)
; #define PG8_WAIT_V(n) asm volatile("s_waitcnt vmcnt(" #n ")" ::: "memory")
; #define PG8_WAIT_L(n) asm volatile("s_waitcnt lgkmcnt(" #n ")" ::: "memory")
; #define PG8_BAR __builtin_amdgcn_s_barrier()
; #define PG8_SCHED __builtin_amdgcn_sched_barrier(0)
; template <class Epi, class Sched, bool ALIGN_EPI = false, bool SP2 = false>
; __device__ __forceinline__ void gemm_phase(PG8_LAS unsigned char* lds, const Gemm g, const Sched& S, const Epi& E) {
;     ...
;             PG8_LDA(At, 1, 1); PG8_STAGE(PG8_SB(1, 0), b3, voffB); PG8_STAGE(PG8_SB(1, 1), b3 + hstep, voffB); PG8_STAGE(PG8_SA(1, 0), a3, voffA);
;             PG8_WAIT_V(8); PG8_WAIT_L(0); PG8_BAR; PG8_MMA(1, 0, At, B0); PG8_MMA(1, 1, At, B1); PG8_BAR; PG8_SCHED;
	s_add_i32 s24, s72, s51
	v_lshl_add_u64 v[148:149], v[148:149], 0, s[38:39]
	s_mov_b32 m0, s24
	ds_read_b128 v[188:191], v152 offset:49152
	ds_read_b128 v[206:209], v152 offset:50176
	ds_read_b128 v[210:213], v152 offset:51200
	ds_read_b128 v[214:217], v152 offset:52224
	ds_read_b128 v[218:221], v152 offset:53248
	ds_read_b128 v[222:225], v152 offset:54272
	ds_read_b128 v[226:229], v152 offset:55296
	ds_read_b128 v[230:233], v152 offset:56320
	global_load_lds_dwordx4 v[148:149], off
	s_add_i32 m0, s24, 0x2000
	s_add_u32 s24, s42, 0x40080
	v_lshl_add_u64 v[148:149], v[234:235], 0, s[38:39]
	s_addc_u32 s25, s43, 0
	s_add_i32 s42, s73, s51
	global_load_lds_dwordx4 v[148:149], off
	v_lshl_add_u64 v[148:149], s[24:25], 0, v[132:133]
	s_mov_b32 m0, s42
	s_nop 0
	global_load_lds_dwordx4 v[148:149], off
	v_lshl_add_u64 v[148:149], s[24:25], 0, v[136:137]
	s_add_i32 m0, s42, 0x2000
	s_nop 0
	global_load_lds_dwordx4 v[148:149], off
	v_lshl_add_u64 v[148:149], s[26:27], 0, v[130:131]
	s_mov_b32 m0, s64
	s_nop 0
	global_load_lds_dwordx4 v[148:149], off
	v_lshl_add_u64 v[148:149], s[26:27], 0, v[134:135]
	s_mov_b32 m0, s65
	s_nop 0
	global_load_lds_dwordx4 v[148:149], off
	s_waitcnt vmcnt(8)
	s_waitcnt lgkmcnt(0)
	s_barrier
	v_mfma_f32_16x16x32_bf16 v[62:65], v[144:147], v[188:191], v[62:65]
	v_mfma_f32_16x16x32_bf16 v[62:65], v[160:163], v[206:209], v[62:65]
	v_mfma_f32_16x16x32_bf16 v[58:61], v[168:171], v[206:209], v[58:61]
	v_mfma_f32_16x16x32_bf16 v[58:61], v[164:167], v[188:191], v[58:61]
	v_mfma_f32_16x16x32_bf16 v[42:45], v[164:167], v[210:213], v[42:45]
	v_mfma_f32_16x16x32_bf16 v[42:45], v[168:171], v[214:217], v[42:45]
	v_mfma_f32_16x16x32_bf16 v[46:49], v[160:163], v[214:217], v[46:49]
	v_mfma_f32_16x16x32_bf16 v[46:49], v[144:147], v[210:213], v[46:49]
	v_mfma_f32_16x16x32_bf16 v[30:33], v[144:147], v[218:221], v[30:33]
	v_mfma_f32_16x16x32_bf16 v[30:33], v[160:163], v[222:225], v[30:33]
	v_mfma_f32_16x16x32_bf16 v[26:29], v[168:171], v[222:225], v[26:29]
	v_mfma_f32_16x16x32_bf16 v[26:29], v[164:167], v[218:221], v[26:29]
	v_mfma_f32_16x16x32_bf16 v[10:13], v[164:167], v[226:229], v[10:13]
	v_mfma_f32_16x16x32_bf16 v[10:13], v[168:171], v[230:233], v[10:13]
	v_mfma_f32_16x16x32_bf16 v[14:17], v[160:163], v[230:233], v[14:17]
	v_mfma_f32_16x16x32_bf16 v[14:17], v[144:147], v[226:229], v[14:17]
	v_mfma_f32_16x16x32_bf16 v[54:57], v[172:175], v[188:191], v[54:57]
	v_mfma_f32_16x16x32_bf16 v[54:57], v[176:179], v[206:209], v[54:57]
	v_mfma_f32_16x16x32_bf16 v[50:53], v[184:187], v[206:209], v[50:53]
	v_mfma_f32_16x16x32_bf16 v[50:53], v[180:183], v[188:191], v[50:53]
	v_mfma_f32_16x16x32_bf16 v[34:37], v[180:183], v[210:213], v[34:37]
	v_mfma_f32_16x16x32_bf16 v[34:37], v[184:187], v[214:217], v[34:37]
	v_mfma_f32_16x16x32_bf16 v[38:41], v[176:179], v[214:217], v[38:41]
	v_mfma_f32_16x16x32_bf16 v[38:41], v[172:175], v[210:213], v[38:41]
	v_mfma_f32_16x16x32_bf16 v[22:25], v[172:175], v[218:221], v[22:25]
	v_mfma_f32_16x16x32_bf16 v[22:25], v[176:179], v[222:225], v[22:25]
	v_mfma_f32_16x16x32_bf16 v[18:21], v[184:187], v[222:225], v[18:21]
	v_mfma_f32_16x16x32_bf16 v[18:21], v[180:183], v[218:221], v[18:21]
	v_mfma_f32_16x16x32_bf16 v[2:5], v[180:183], v[226:229], v[2:5]
	v_mfma_f32_16x16x32_bf16 v[2:5], v[184:187], v[230:233], v[2:5]
	v_mfma_f32_16x16x32_bf16 v[6:9], v[176:179], v[230:233], v[6:9]
	v_mfma_f32_16x16x32_bf16 v[6:9], v[172:175], v[226:229], v[6:9]
	s_barrier
	s_add_i32 s71, s71, 2
	s_add_u32 s69, s69, 0x100
	s_addc_u32 s70, s70, 0
	s_cmp_gt_u32 s71, 13
	s_mov_b64 s[24:25], s[2:3]
	s_cbranch_scc0 .LBB0_238
	s_and_b64 vcc, exec, s[6:7]
	s_cbranch_vccz .LBB0_241
	s_barrier

; #define PG8_STAGE(bufoff, gbase, voff) do { _Pragma("unroll") for (int _i = 0; _i < 2; ++_i) \
;         __builtin_amdgcn_global_load_lds((const unsigned*)((const char*)(gbase) + (voff)[_i]), (PG8_LAS unsigned*)(lds + (bufoff) + ldsw + _i * 8192), 16, 0, 0); } while (0)
; #define PG8_LDA(dst, b, h) do { _Pragma("unroll") for (int m = 0; m < 4; ++m) _Pragma("unroll") for (int k = 0; k < 2; ++k) dst[m][k] = *(const PG8_LAS bf16x8*)(lds + PG8_SA(b, h) + aoff + m * 2048 + k * 1024); } while (0)
; #define PG8_LDB(dst, b, h) do { _Pragma("unroll") for (int n = 0; n < 2; ++n) _Pragma("unroll") for (int k = 0; k < 2; ++k) dst[n][k] = *(const PG8_LAS bf16x8*)(lds + PG8_SB(b, h) + boff + n * 2048 + k * 1024); } while (0)
; #define PG8_MMA(ai, bj, At, Bt) do { __builtin_amdgcn_s_setprio(1); _Pragma("unroll") for (int m = 0; m < 4; ++m) _Pragma("unroll") for (int n = 0; n < 2; ++n) _Pragma("unroll") for (int k = 0; k < 2; ++k) \
;         acc[ai][bj][m][n] = __builtin_amdgcn_mfma_f32_16x16x32_bf16(Bt[n][k], At[m][k], acc[ai][bj][m][n], 0, 0, 0); __builtin_amdgcn_s_setprio(0); } while (0)
; #define PG8_WAIT_V(n) asm volatile("s_waitcnt vmcnt(" #n ")" ::: "memory")
; #define PG8_WAIT_L(n) asm volatile("s_waitcnt lgkmcnt(" #n ")" ::: "memory")
; template <class Epi, class Sched, bool ALIGN_EPI = false, bool SP2 = false>
; __device__ __forceinline__ void gemm_phase(PG8_LAS unsigned char* lds, const Gemm g, const Sched& S, const Epi& E) {
;     ...
;             const bool last = (t == nt - 2);
;             const char* a1 = cA + (size_t)(t + 1) * kstepA;
;             const char* a2 = last ? nA : cA + (size_t)(t + 2) * kstepA; const char* b2 = last ? nB : cB + (size_t)(t + 2) * kstep;
;             const char* a3 = a2 + kstepA; const char* b3 = b2 + kstep;
;             if (last && has_next) S.a_ready(nxt);
;             if constexpr (SP2) {
;             PG8_LDB(B0, 0, 0); PG8_LDB(B1, 0, 1); PG8_SCHED; PG8_LDA(At, 0, 0); PG8_STAGE(PG8_SA(1, 1), a1 + hstep, voffA);
;             PG8_WAIT_V(8); PG8_WAIT_L(0); PG8_BAR; PG8_MMA(0, 0, At, B0); PG8_MMA(0, 1, At, B1); PG8_BAR; PG8_SCHED;
;             PG8_LDA(At, 0, 1); PG8_STAGE(PG8_SB(0, 0), b2, voffB); PG8_STAGE(PG8_SB(0, 1), b2 + hstep, voffB); PG8_STAGE(PG8_SA(0, 0), a2, voffA);
;             PG8_WAIT_V(8); PG8_WAIT_L(0); PG8_BAR; PG8_MMA(1, 0, At, B0); PG8_MMA(1, 1, At, B1); PG8_BAR; PG8_SCHED;
.LBB0_310:
	s_add_i32 s49, s24, 2
	s_add_u32 s25, s2, 0x4000
	s_addc_u32 s26, s3, 0
	s_cmp_eq_u32 s59, s24
	s_cselect_b32 s27, s9, s26
	s_cselect_b32 s26, s8, s25
	s_cselect_b32 s66, s44, s47
	s_cselect_b32 s67, s45, s48
	s_add_u32 s24, s26, 0x4000
	s_addc_u32 s25, s27, 0
	s_add_i32 s65, 0, 0x14000
	v_add_u32_e32 v142, s76, v187
	v_add_u32_e32 v167, s65, v187
	ds_read_b128 v[130:133], v142
	ds_read_b128 v[134:137], v142 offset:1024
	ds_read_b128 v[138:141], v142 offset:2048
	ds_read_b128 v[142:145], v142 offset:3072
	ds_read_b128 v[146:149], v167
	ds_read_b128 v[150:153], v167 offset:1024
	ds_read_b128 v[206:209], v167 offset:2048
	ds_read_b128 v[210:213], v167 offset:3072
	v_lshl_add_u64 v[184:185], s[2:3], 0, v[182:183]
	s_add_i32 m0, s51, 0xc000
	ds_read_b128 v[214:217], v188
	ds_read_b128 v[218:221], v188 offset:1024
	ds_read_b128 v[222:225], v188 offset:2048
	ds_read_b128 v[226:229], v188 offset:3072
	ds_read_b128 v[230:233], v188 offset:4096
	ds_read_b128 v[234:237], v188 offset:5120
	ds_read_b128 v[238:241], v188 offset:6144
	ds_read_b128 v[242:245], v188 offset:7168
	global_load_lds_dwordx4 v[184:185], off
	v_lshl_add_u64 v[184:185], s[2:3], 0, v[180:181]
	s_add_i32 m0, s51, 0xe000
	s_nop 0
	global_load_lds_dwordx4 v[184:185], off
	s_waitcnt vmcnt(8)
	s_waitcnt lgkmcnt(0)
	s_barrier
	v_mfma_f32_16x16x32_bf16 v[126:129], v[130:133], v[214:217], v[126:129]
	v_mfma_f32_16x16x32_bf16 v[126:129], v[134:137], v[218:221], v[126:129]
	v_mfma_f32_16x16x32_bf16 v[122:125], v[142:145], v[218:221], v[122:125]
	v_mfma_f32_16x16x32_bf16 v[122:125], v[138:141], v[214:217], v[122:125]
	v_mfma_f32_16x16x32_bf16 v[106:109], v[138:141], v[222:225], v[106:109]
	v_mfma_f32_16x16x32_bf16 v[106:109], v[142:145], v[226:229], v[106:109]
	v_mfma_f32_16x16x32_bf16 v[110:113], v[134:137], v[226:229], v[110:113]
	v_mfma_f32_16x16x32_bf16 v[110:113], v[130:133], v[222:225], v[110:113]
	v_mfma_f32_16x16x32_bf16 v[94:97], v[130:133], v[230:233], v[94:97]
	v_mfma_f32_16x16x32_bf16 v[94:97], v[134:137], v[234:237], v[94:97]
	v_mfma_f32_16x16x32_bf16 v[90:93], v[142:145], v[234:237], v[90:93]
	v_mfma_f32_16x16x32_bf16 v[90:93], v[138:141], v[230:233], v[90:93]
	v_mfma_f32_16x16x32_bf16 v[74:77], v[138:141], v[238:241], v[74:77]
	v_mfma_f32_16x16x32_bf16 v[74:77], v[142:145], v[242:245], v[74:77]
	v_mfma_f32_16x16x32_bf16 v[78:81], v[134:137], v[242:245], v[78:81]
	v_mfma_f32_16x16x32_bf16 v[78:81], v[130:133], v[238:241], v[78:81]
	v_mfma_f32_16x16x32_bf16 v[118:121], v[146:149], v[214:217], v[118:121]
	v_mfma_f32_16x16x32_bf16 v[118:121], v[150:153], v[218:221], v[118:121]
	v_mfma_f32_16x16x32_bf16 v[114:117], v[210:213], v[218:221], v[114:117]
	v_mfma_f32_16x16x32_bf16 v[114:117], v[206:209], v[214:217], v[114:117]
	v_mfma_f32_16x16x32_bf16 v[98:101], v[206:209], v[222:225], v[98:101]
	v_mfma_f32_16x16x32_bf16 v[98:101], v[210:213], v[226:229], v[98:101]
	v_mfma_f32_16x16x32_bf16 v[102:105], v[150:153], v[226:229], v[102:105]
	v_mfma_f32_16x16x32_bf16 v[102:105], v[146:149], v[222:225], v[102:105]
	v_mfma_f32_16x16x32_bf16 v[86:89], v[146:149], v[230:233], v[86:89]
	v_mfma_f32_16x16x32_bf16 v[86:89], v[150:153], v[234:237], v[86:89]
	v_mfma_f32_16x16x32_bf16 v[82:85], v[210:213], v[234:237], v[82:85]
	v_mfma_f32_16x16x32_bf16 v[82:85], v[206:209], v[230:233], v[82:85]
	v_mfma_f32_16x16x32_bf16 v[66:69], v[206:209], v[238:241], v[66:69]
	v_mfma_f32_16x16x32_bf16 v[66:69], v[210:213], v[242:245], v[66:69]
	v_mfma_f32_16x16x32_bf16 v[70:73], v[150:153], v[242:245], v[70:73]
	v_mfma_f32_16x16x32_bf16 v[70:73], v[146:149], v[238:241], v[70:73]
	s_barrier
	s_add_i32 s68, s76, s50
	v_lshl_add_u64 v[184:185], s[66:67], 0, v[0:1]
	s_mov_b32 m0, s68
	ds_read_b128 v[214:217], v188 offset:16384
	ds_read_b128 v[218:221], v188 offset:17408
	ds_read_b128 v[222:225], v188 offset:18432
	ds_read_b128 v[226:229], v188 offset:19456
	ds_read_b128 v[230:233], v188 offset:20480
	ds_read_b128 v[234:237], v188 offset:21504
	ds_read_b128 v[238:241], v188 offset:22528
	ds_read_b128 v[242:245], v188 offset:23552
	global_load_lds_dwordx4 v[184:185], off
	s_add_i32 m0, s68, 0x2000
	v_lshl_add_u64 v[190:191], s[66:67], 0, v[164:165]
	s_add_u32 s66, s66, s12
	s_addc_u32 s67, s67, 0
	s_add_i32 s65, s65, s50
	global_load_lds_dwordx4 v[190:191], off
	v_lshl_add_u64 v[246:247], s[66:67], 0, v[0:1]
	s_mov_b32 m0, s65
	v_lshl_add_u64 v[248:249], s[66:67], 0, v[164:165]
	global_load_lds_dwordx4 v[246:247], off
	s_add_i32 m0, s65, 0x2000
	v_lshl_add_u64 v[250:251], s[26:27], 0, v[160:161]
	global_load_lds_dwordx4 v[248:249], off
	s_mov_b32 m0, s51
	s_nop 0
	global_load_lds_dwordx4 v[250:251], off
	v_lshl_add_u64 v[250:251], s[26:27], 0, v[162:163]
	s_mov_b32 m0, s52
	s_nop 0
	global_load_lds_dwordx4 v[250:251], off
	s_waitcnt vmcnt(8)
	s_waitcnt lgkmcnt(0)
	s_barrier
; #define PG8_STAGE(bufoff, gbase, voff) do { _Pragma("unroll") for (int _i = 0; _i < 2; ++_i) \
;         __builtin_amdgcn_global_load_lds((const unsigned*)((const char*)(gbase) + (voff)[_i]), (PG8_LAS unsigned*)(lds + (bufoff) + ldsw + _i * 8192), 16, 0, 0); } while (0)
; #define PG8_LDA(dst, b, h) do { _Pragma("unroll") for (int m = 0; m < 4; ++m) _Pragma("unroll") for (int k = 0; k < 2; ++k) dst[m][k] = *(const PG8_LAS bf16x8*)(lds + PG8_SA(b, h) + aoff + m * 2048 + k * 1024); } while (0)
; #define PG8_LDB(dst, b, h) do { _Pragma("unroll") for (int n = 0; n < 2; ++n) _Pragma("unroll") for (int k = 0; k < 2; ++k) dst[n][k] = *(const PG8_LAS bf16x8*)(lds + PG8_SB(b, h) + boff + n * 2048 + k * 1024); } while (0)
; #define PG8_MMA(ai, bj, At, Bt) do { __builtin_amdgcn_s_setprio(1); _Pragma("unroll") for (int m = 0; m < 4; ++m) _Pragma("unroll") for (int n = 0; n < 2; ++n) _Pragma("unroll") for (int k = 0; k < 2; ++k) \
;         acc[ai][bj][m][n] = __builtin_amdgcn_mfma_f32_16x16x32_bf16(Bt[n][k], At[m][k], acc[ai][bj][m][n], 0, 0, 0); __builtin_amdgcn_s_setprio(0); } while (0)
; #define PG8_WAIT_V(n) asm volatile("s_waitcnt vmcnt(" #n ")" ::: "memory")
; #define PG8_WAIT_L(n) asm volatile("s_waitcnt lgkmcnt(" #n ")" ::: "memory")
; #define PG8_BAR __builtin_amdgcn_s_barrier()
; #define PG8_SCHED __builtin_amdgcn_sched_barrier(0)
; template <class Epi, class Sched, bool ALIGN_EPI = false, bool SP2 = false>
; __device__ __forceinline__ void gemm_phase(PG8_LAS unsigned char* lds, const Gemm g, const Sched& S, const Epi& E) {
;     ...
;             PG8_WAIT_V(8); PG8_WAIT_L(0); PG8_BAR; PG8_MMA(1, 0, At, B0); PG8_MMA(1, 1, At, B1); PG8_BAR; PG8_SCHED;
;             PG8_LDB(B0, 1, 0); PG8_LDB(B1, 1, 1); PG8_SCHED; PG8_LDA(At, 1, 0); PG8_STAGE(PG8_SA(0, 1), a2 + hstep, voffA);
;             PG8_WAIT_V(8); PG8_WAIT_L(0); PG8_BAR; PG8_MMA(0, 0, At, B0); PG8_MMA(0, 1, At, B1); PG8_BAR; PG8_SCHED;
	v_mfma_f32_16x16x32_bf16 v[62:65], v[130:133], v[214:217], v[62:65]
	v_mfma_f32_16x16x32_bf16 v[62:65], v[134:137], v[218:221], v[62:65]
	v_mfma_f32_16x16x32_bf16 v[58:61], v[142:145], v[218:221], v[58:61]
	v_mfma_f32_16x16x32_bf16 v[58:61], v[138:141], v[214:217], v[58:61]
	v_mfma_f32_16x16x32_bf16 v[42:45], v[138:141], v[222:225], v[42:45]
	v_mfma_f32_16x16x32_bf16 v[42:45], v[142:145], v[226:229], v[42:45]
	v_mfma_f32_16x16x32_bf16 v[46:49], v[134:137], v[226:229], v[46:49]
	v_mfma_f32_16x16x32_bf16 v[46:49], v[130:133], v[222:225], v[46:49]
	v_mfma_f32_16x16x32_bf16 v[30:33], v[130:133], v[230:233], v[30:33]
	v_mfma_f32_16x16x32_bf16 v[30:33], v[134:137], v[234:237], v[30:33]
	v_mfma_f32_16x16x32_bf16 v[26:29], v[142:145], v[234:237], v[26:29]
	v_mfma_f32_16x16x32_bf16 v[26:29], v[138:141], v[230:233], v[26:29]
	v_mfma_f32_16x16x32_bf16 v[10:13], v[138:141], v[238:241], v[10:13]
	v_mfma_f32_16x16x32_bf16 v[10:13], v[142:145], v[242:245], v[10:13]
	v_mfma_f32_16x16x32_bf16 v[14:17], v[134:137], v[242:245], v[14:17]
	v_mfma_f32_16x16x32_bf16 v[14:17], v[130:133], v[238:241], v[14:17]
	v_mfma_f32_16x16x32_bf16 v[54:57], v[146:149], v[214:217], v[54:57]
	v_mfma_f32_16x16x32_bf16 v[54:57], v[150:153], v[218:221], v[54:57]
	v_mfma_f32_16x16x32_bf16 v[50:53], v[210:213], v[218:221], v[50:53]
	v_mfma_f32_16x16x32_bf16 v[50:53], v[206:209], v[214:217], v[50:53]
	v_mfma_f32_16x16x32_bf16 v[34:37], v[206:209], v[222:225], v[34:37]
	v_mfma_f32_16x16x32_bf16 v[34:37], v[210:213], v[226:229], v[34:37]
	v_mfma_f32_16x16x32_bf16 v[38:41], v[150:153], v[226:229], v[38:41]
	v_mfma_f32_16x16x32_bf16 v[38:41], v[146:149], v[222:225], v[38:41]
	v_mfma_f32_16x16x32_bf16 v[22:25], v[146:149], v[230:233], v[22:25]
	v_mfma_f32_16x16x32_bf16 v[22:25], v[150:153], v[234:237], v[22:25]
	v_mfma_f32_16x16x32_bf16 v[18:21], v[210:213], v[234:237], v[18:21]
	v_mfma_f32_16x16x32_bf16 v[18:21], v[206:209], v[230:233], v[18:21]
	v_mfma_f32_16x16x32_bf16 v[2:5], v[206:209], v[238:241], v[2:5]
	v_mfma_f32_16x16x32_bf16 v[2:5], v[210:213], v[242:245], v[2:5]
	v_mfma_f32_16x16x32_bf16 v[6:9], v[150:153], v[242:245], v[6:9]
	v_mfma_f32_16x16x32_bf16 v[6:9], v[146:149], v[238:241], v[6:9]
	s_barrier
	s_add_i32 s65, 0, 0x18000
	s_add_i32 s66, 0, 0x1c000
	v_add_u32_e32 v142, s65, v187
	v_add_u32_e32 v167, s66, v187
	ds_read_b128 v[130:133], v142
	ds_read_b128 v[134:137], v142 offset:1024
	ds_read_b128 v[138:141], v142 offset:2048
	ds_read_b128 v[142:145], v142 offset:3072
	ds_read_b128 v[146:149], v167
	ds_read_b128 v[150:153], v167 offset:1024
	ds_read_b128 v[206:209], v167 offset:2048
	ds_read_b128 v[210:213], v167 offset:3072
	s_add_u32 s26, s26, s12
	s_addc_u32 s27, s27, 0
	s_mov_b32 m0, s53
	v_lshl_add_u64 v[250:251], s[26:27], 0, v[160:161]
	ds_read_b128 v[214:217], v188 offset:32768
	ds_read_b128 v[218:221], v188 offset:33792
	ds_read_b128 v[222:225], v188 offset:34816
	ds_read_b128 v[226:229], v188 offset:35840
	ds_read_b128 v[230:233], v188 offset:36864
	ds_read_b128 v[234:237], v188 offset:37888
	ds_read_b128 v[238:241], v188 offset:38912
	ds_read_b128 v[242:245], v188 offset:39936
	global_load_lds_dwordx4 v[250:251], off
	v_lshl_add_u64 v[250:251], s[26:27], 0, v[162:163]
	s_mov_b32 m0, s54
	s_nop 0
	global_load_lds_dwordx4 v[250:251], off
	s_waitcnt vmcnt(8)
	s_waitcnt lgkmcnt(0)
	s_barrier
	v_mfma_f32_16x16x32_bf16 v[126:129], v[130:133], v[214:217], v[126:129]
	v_mfma_f32_16x16x32_bf16 v[126:129], v[134:137], v[218:221], v[126:129]
	v_mfma_f32_16x16x32_bf16 v[122:125], v[142:145], v[218:221], v[122:125]
	v_mfma_f32_16x16x32_bf16 v[122:125], v[138:141], v[214:217], v[122:125]
	v_mfma_f32_16x16x32_bf16 v[106:109], v[138:141], v[222:225], v[106:109]
	v_mfma_f32_16x16x32_bf16 v[106:109], v[142:145], v[226:229], v[106:109]
	v_mfma_f32_16x16x32_bf16 v[110:113], v[134:137], v[226:229], v[110:113]
	v_mfma_f32_16x16x32_bf16 v[110:113], v[130:133], v[222:225], v[110:113]
	v_mfma_f32_16x16x32_bf16 v[94:97], v[130:133], v[230:233], v[94:97]
	v_mfma_f32_16x16x32_bf16 v[94:97], v[134:137], v[234:237], v[94:97]
	v_mfma_f32_16x16x32_bf16 v[90:93], v[142:145], v[234:237], v[90:93]
	v_mfma_f32_16x16x32_bf16 v[90:93], v[138:141], v[230:233], v[90:93]
	v_mfma_f32_16x16x32_bf16 v[74:77], v[138:141], v[238:241], v[74:77]
	v_mfma_f32_16x16x32_bf16 v[74:77], v[142:145], v[242:245], v[74:77]
	v_mfma_f32_16x16x32_bf16 v[78:81], v[134:137], v[242:245], v[78:81]
	v_mfma_f32_16x16x32_bf16 v[78:81], v[130:133], v[238:241], v[78:81]
	v_mfma_f32_16x16x32_bf16 v[118:121], v[146:149], v[214:217], v[118:121]
	v_mfma_f32_16x16x32_bf16 v[118:121], v[150:153], v[218:221], v[118:121]
	v_mfma_f32_16x16x32_bf16 v[114:117], v[210:213], v[218:221], v[114:117]
	v_mfma_f32_16x16x32_bf16 v[114:117], v[206:209], v[214:217], v[114:117]
	v_mfma_f32_16x16x32_bf16 v[98:101], v[206:209], v[222:225], v[98:101]
	v_mfma_f32_16x16x32_bf16 v[98:101], v[210:213], v[226:229], v[98:101]
	v_mfma_f32_16x16x32_bf16 v[102:105], v[150:153], v[226:229], v[102:105]
	v_mfma_f32_16x16x32_bf16 v[102:105], v[146:149], v[222:225], v[102:105]
	v_mfma_f32_16x16x32_bf16 v[86:89], v[146:149], v[230:233], v[86:89]
	v_mfma_f32_16x16x32_bf16 v[86:89], v[150:153], v[234:237], v[86:89]
	v_mfma_f32_16x16x32_bf16 v[82:85], v[210:213], v[234:237], v[82:85]
	v_mfma_f32_16x16x32_bf16 v[82:85], v[206:209], v[230:233], v[82:85]
	v_mfma_f32_16x16x32_bf16 v[66:69], v[206:209], v[238:241], v[66:69]
	v_mfma_f32_16x16x32_bf16 v[66:69], v[210:213], v[242:245], v[66:69]
	v_mfma_f32_16x16x32_bf16 v[70:73], v[150:153], v[242:245], v[70:73]
	v_mfma_f32_16x16x32_bf16 v[70:73], v[146:149], v[238:241], v[70:73]
	s_barrier
; #define PG8_STAGE(bufoff, gbase, voff) do { _Pragma("unroll") for (int _i = 0; _i < 2; ++_i) \
;         __builtin_amdgcn_global_load_lds((const unsigned*)((const char*)(gbase) + (voff)[_i]), (PG8_LAS unsigned*)(lds + (bufoff) + ldsw + _i * 8192), 16, 0, 0); } while (0)
; #define PG8_LDA(dst, b, h) do { _Pragma("unroll") for (int m = 0; m < 4; ++m) _Pragma("unroll") for (int k = 0; k < 2; ++k) dst[m][k] = *(const PG8_LAS bf16x8*)(lds + PG8_SA(b, h) + aoff + m * 2048 + k * 1024); } while (0)
; #define PG8_MMA(ai, bj, At, Bt) do { __builtin_amdgcn_s_setprio(1); _Pragma("unroll") for (int m = 0; m < 4; ++m) _Pragma("unroll") for (int n = 0; n < 2; ++n) _Pragma("unroll") for (int k = 0; k < 2; ++k) \
;         acc[ai][bj][m][n] = __builtin_amdgcn_mfma_f32_16x16x32_bf16(Bt[n][k], At[m][k], acc[ai][bj][m][n], 0, 0, 0); __builtin_amdgcn_s_setprio(0); } while (0)
; #define PG8_WAIT_V(n) asm volatile("s_waitcnt vmcnt(" #n ")" ::: "memory")
; #define PG8_WAIT_L(n) asm volatile("s_waitcnt lgkmcnt(" #n ")" ::: "memory")
; #define PG8_BAR __builtin_amdgcn_s_barrier()
; #define PG8_SCHED __builtin_amdgcn_sched_barrier(0)
; template <class Epi, class Sched, bool ALIGN_EPI = false, bool SP2 = false>
; __device__ __forceinline__ void gemm_phase(PG8_LAS unsigned char* lds, const Gemm g, const Sched& S, const Epi& E) {
;     ...
;             PG8_LDA(At, 1, 1); PG8_STAGE(PG8_SB(1, 0), b3, voffB); PG8_STAGE(PG8_SB(1, 1), b3 + hstep, voffB); PG8_STAGE(PG8_SA(1, 0), a3, voffA);
;             PG8_WAIT_V(8); PG8_WAIT_L(0); PG8_BAR; PG8_MMA(1, 0, At, B0); PG8_MMA(1, 1, At, B1); PG8_BAR; PG8_SCHED;
;     ...
;         if constexpr (ALIGN_EPI) { if (wr == 0) PG8_BAR; }
	s_add_i32 s26, s65, s50
	v_lshl_add_u64 v[184:185], v[184:185], 0, s[38:39]
	s_mov_b32 m0, s26
	ds_read_b128 v[214:217], v188 offset:49152
	ds_read_b128 v[218:221], v188 offset:50176
	ds_read_b128 v[222:225], v188 offset:51200
	ds_read_b128 v[226:229], v188 offset:52224
	ds_read_b128 v[230:233], v188 offset:53248
	ds_read_b128 v[234:237], v188 offset:54272
	ds_read_b128 v[238:241], v188 offset:55296
	ds_read_b128 v[242:245], v188 offset:56320
	global_load_lds_dwordx4 v[184:185], off
	v_lshl_add_u64 v[184:185], v[190:191], 0, s[38:39]
	s_add_i32 m0, s26, 0x2000
	s_add_i32 s26, s66, s50
	global_load_lds_dwordx4 v[184:185], off
	v_lshl_add_u64 v[184:185], v[246:247], 0, s[38:39]
	s_mov_b32 m0, s26
	s_nop 0
	global_load_lds_dwordx4 v[184:185], off
	v_lshl_add_u64 v[184:185], v[248:249], 0, s[38:39]
	s_add_i32 m0, s26, 0x2000
	s_nop 0
	global_load_lds_dwordx4 v[184:185], off
	v_lshl_add_u64 v[184:185], s[24:25], 0, v[160:161]
	s_mov_b32 m0, s56
	s_nop 0
	global_load_lds_dwordx4 v[184:185], off
	v_lshl_add_u64 v[184:185], s[24:25], 0, v[162:163]
	s_mov_b32 m0, s57
	s_nop 0
	global_load_lds_dwordx4 v[184:185], off
	s_waitcnt vmcnt(8)
	s_waitcnt lgkmcnt(0)
	s_barrier
	v_mfma_f32_16x16x32_bf16 v[62:65], v[130:133], v[214:217], v[62:65]
	v_mfma_f32_16x16x32_bf16 v[62:65], v[134:137], v[218:221], v[62:65]
	v_mfma_f32_16x16x32_bf16 v[58:61], v[142:145], v[218:221], v[58:61]
	v_mfma_f32_16x16x32_bf16 v[58:61], v[138:141], v[214:217], v[58:61]
	v_mfma_f32_16x16x32_bf16 v[42:45], v[138:141], v[222:225], v[42:45]
	v_mfma_f32_16x16x32_bf16 v[42:45], v[142:145], v[226:229], v[42:45]
	v_mfma_f32_16x16x32_bf16 v[46:49], v[134:137], v[226:229], v[46:49]
	v_mfma_f32_16x16x32_bf16 v[46:49], v[130:133], v[222:225], v[46:49]
	v_mfma_f32_16x16x32_bf16 v[30:33], v[130:133], v[230:233], v[30:33]
	v_mfma_f32_16x16x32_bf16 v[30:33], v[134:137], v[234:237], v[30:33]
	v_mfma_f32_16x16x32_bf16 v[26:29], v[142:145], v[234:237], v[26:29]
	v_mfma_f32_16x16x32_bf16 v[26:29], v[138:141], v[230:233], v[26:29]
	v_mfma_f32_16x16x32_bf16 v[10:13], v[138:141], v[238:241], v[10:13]
	v_mfma_f32_16x16x32_bf16 v[10:13], v[142:145], v[242:245], v[10:13]
	v_mfma_f32_16x16x32_bf16 v[14:17], v[134:137], v[242:245], v[14:17]
	v_mfma_f32_16x16x32_bf16 v[14:17], v[130:133], v[238:241], v[14:17]
	v_mfma_f32_16x16x32_bf16 v[54:57], v[146:149], v[214:217], v[54:57]
	v_mfma_f32_16x16x32_bf16 v[54:57], v[150:153], v[218:221], v[54:57]
	v_mfma_f32_16x16x32_bf16 v[50:53], v[210:213], v[218:221], v[50:53]
	v_mfma_f32_16x16x32_bf16 v[50:53], v[206:209], v[214:217], v[50:53]
	v_mfma_f32_16x16x32_bf16 v[34:37], v[206:209], v[222:225], v[34:37]
	v_mfma_f32_16x16x32_bf16 v[34:37], v[210:213], v[226:229], v[34:37]
	v_mfma_f32_16x16x32_bf16 v[38:41], v[150:153], v[226:229], v[38:41]
	v_mfma_f32_16x16x32_bf16 v[38:41], v[146:149], v[222:225], v[38:41]
	v_mfma_f32_16x16x32_bf16 v[22:25], v[146:149], v[230:233], v[22:25]
	v_mfma_f32_16x16x32_bf16 v[22:25], v[150:153], v[234:237], v[22:25]
	v_mfma_f32_16x16x32_bf16 v[18:21], v[210:213], v[234:237], v[18:21]
	v_mfma_f32_16x16x32_bf16 v[18:21], v[206:209], v[230:233], v[18:21]
	v_mfma_f32_16x16x32_bf16 v[2:5], v[206:209], v[238:241], v[2:5]
	v_mfma_f32_16x16x32_bf16 v[2:5], v[210:213], v[242:245], v[2:5]
	v_mfma_f32_16x16x32_bf16 v[6:9], v[150:153], v[242:245], v[6:9]
	v_mfma_f32_16x16x32_bf16 v[6:9], v[146:149], v[238:241], v[6:9]
	s_barrier
	s_add_u32 s47, s47, 0x100
	s_addc_u32 s48, s48, 0
	s_add_u32 s2, s2, 0x8000
	s_addc_u32 s3, s3, 0
	s_cmp_ge_u32 s49, s55
	s_mov_b32 s24, s49
	s_cbranch_scc0 .LBB0_310
	s_and_b64 vcc, exec, s[42:43]
	s_cbranch_vccz .LBB0_313
	s_barrier

; #define PG8_STAGE(bufoff, gbase, voff) do { _Pragma("unroll") for (int _i = 0; _i < 2; ++_i) \
;         __builtin_amdgcn_global_load_lds((const unsigned*)((const char*)(gbase) + (voff)[_i]), (PG8_LAS unsigned*)(lds + (bufoff) + ldsw + _i * 8192), 16, 0, 0); } while (0)
; #define PG8_LDA(dst, b, h) do { _Pragma("unroll") for (int m = 0; m < 4; ++m) _Pragma("unroll") for (int k = 0; k < 2; ++k) dst[m][k] = *(const PG8_LAS bf16x8*)(lds + PG8_SA(b, h) + aoff + m * 2048 + k * 1024); } while (0)
; #define PG8_LDB(dst, b, h) do { _Pragma("unroll") for (int n = 0; n < 2; ++n) _Pragma("unroll") for (int k = 0; k < 2; ++k) dst[n][k] = *(const PG8_LAS bf16x8*)(lds + PG8_SB(b, h) + boff + n * 2048 + k * 1024); } while (0)
; #define PG8_MMA(ai, bj, At, Bt) do { __builtin_amdgcn_s_setprio(1); _Pragma("unroll") for (int m = 0; m < 4; ++m) _Pragma("unroll") for (int n = 0; n < 2; ++n) _Pragma("unroll") for (int k = 0; k < 2; ++k) \
;         acc[ai][bj][m][n] = __builtin_amdgcn_mfma_f32_16x16x32_bf16(Bt[n][k], At[m][k], acc[ai][bj][m][n], 0, 0, 0); __builtin_amdgcn_s_setprio(0); } while (0)
; #define PG8_WAIT_V(n) asm volatile("s_waitcnt vmcnt(" #n ")" ::: "memory")
; #define PG8_WAIT_L(n) asm volatile("s_waitcnt lgkmcnt(" #n ")" ::: "memory")
; template <class Epi, class Sched, bool ALIGN_EPI = false, bool SP2 = false>
; __device__ __forceinline__ void gemm_phase(PG8_LAS unsigned char* lds, const Gemm g, const Sched& S, const Epi& E) {
;     ...
;             const bool last = (t == nt - 2);
;             const char* a1 = cA + (size_t)(t + 1) * kstepA;
;             const char* a2 = last ? nA : cA + (size_t)(t + 2) * kstepA; const char* b2 = last ? nB : cB + (size_t)(t + 2) * kstep;
;             const char* a3 = a2 + kstepA; const char* b3 = b2 + kstep;
;             if (last && has_next) S.a_ready(nxt);
;             if constexpr (SP2) {
;             PG8_LDB(B0, 0, 0); PG8_LDB(B1, 0, 1); PG8_SCHED; PG8_LDA(At, 0, 0); PG8_STAGE(PG8_SA(1, 1), a1 + hstep, voffA);
;             PG8_WAIT_V(8); PG8_WAIT_L(0); PG8_BAR; PG8_MMA(0, 0, At, B0); PG8_MMA(0, 1, At, B1); PG8_BAR; PG8_SCHED;
;             PG8_LDA(At, 0, 1); PG8_STAGE(PG8_SB(0, 0), b2, voffB); PG8_STAGE(PG8_SB(0, 1), b2 + hstep, voffB); PG8_STAGE(PG8_SA(0, 0), a2, voffA);
;             PG8_WAIT_V(8); PG8_WAIT_L(0); PG8_BAR; PG8_MMA(1, 0, At, B0); PG8_MMA(1, 1, At, B1); PG8_BAR; PG8_SCHED;
.LBB0_409:
	s_add_u32 s24, s22, 0x8000
	s_addc_u32 s25, s23, 0
	s_cmp_eq_u32 s57, 12
	s_cselect_b32 s42, s53, s24
	s_cselect_b32 s43, s11, s25
	s_cselect_b32 s40, s54, s55
	s_cselect_b32 s41, s9, s56
	s_add_u32 s26, s42, 0x4000
	s_addc_u32 s27, s43, 0
	v_add_u32_e32 v145, s76, v142
	s_add_i32 s58, 0, 0x14000
	ds_read_b128 v[146:149], v145
	ds_read_b128 v[150:153], v145 offset:1024
	ds_read_b128 v[160:163], v145 offset:2048
	ds_read_b128 v[164:167], v145 offset:3072
	v_add_u32_e32 v145, s58, v142
	ds_read_b128 v[168:171], v145
	ds_read_b128 v[172:175], v145 offset:1024
	ds_read_b128 v[176:179], v145 offset:2048
	ds_read_b128 v[180:183], v145 offset:3072
	v_lshl_add_u64 v[230:231], s[22:23], 0, v[140:141]
	s_add_i32 m0, s45, 0xc000
	ds_read_b128 v[184:187], v144
	ds_read_b128 v[188:191], v144 offset:1024
	ds_read_b128 v[206:209], v144 offset:2048
	ds_read_b128 v[210:213], v144 offset:3072
	ds_read_b128 v[214:217], v144 offset:4096
	ds_read_b128 v[218:221], v144 offset:5120
	ds_read_b128 v[222:225], v144 offset:6144
	ds_read_b128 v[226:229], v144 offset:7168
	global_load_lds_dwordx4 v[230:231], off
	v_lshl_add_u64 v[230:231], s[22:23], 0, v[138:139]
	s_add_i32 m0, s45, 0xe000
	s_nop 0
	global_load_lds_dwordx4 v[230:231], off
	s_waitcnt vmcnt(8)
	s_waitcnt lgkmcnt(0)
	s_barrier
	v_mfma_f32_16x16x32_bf16 v[126:129], v[146:149], v[184:187], v[126:129]
	v_mfma_f32_16x16x32_bf16 v[126:129], v[150:153], v[188:191], v[126:129]
	v_mfma_f32_16x16x32_bf16 v[118:121], v[164:167], v[188:191], v[118:121]
	v_mfma_f32_16x16x32_bf16 v[118:121], v[160:163], v[184:187], v[118:121]
	v_mfma_f32_16x16x32_bf16 v[102:105], v[160:163], v[206:209], v[102:105]
	v_mfma_f32_16x16x32_bf16 v[102:105], v[164:167], v[210:213], v[102:105]
	v_mfma_f32_16x16x32_bf16 v[110:113], v[150:153], v[210:213], v[110:113]
	v_mfma_f32_16x16x32_bf16 v[110:113], v[146:149], v[206:209], v[110:113]
	v_mfma_f32_16x16x32_bf16 v[94:97], v[146:149], v[214:217], v[94:97]
	v_mfma_f32_16x16x32_bf16 v[94:97], v[150:153], v[218:221], v[94:97]
	v_mfma_f32_16x16x32_bf16 v[86:89], v[164:167], v[218:221], v[86:89]
	v_mfma_f32_16x16x32_bf16 v[86:89], v[160:163], v[214:217], v[86:89]
	v_mfma_f32_16x16x32_bf16 v[70:73], v[160:163], v[222:225], v[70:73]
	v_mfma_f32_16x16x32_bf16 v[70:73], v[164:167], v[226:229], v[70:73]
	v_mfma_f32_16x16x32_bf16 v[78:81], v[150:153], v[226:229], v[78:81]
	v_mfma_f32_16x16x32_bf16 v[78:81], v[146:149], v[222:225], v[78:81]
	v_mfma_f32_16x16x32_bf16 v[122:125], v[168:171], v[184:187], v[122:125]
	v_mfma_f32_16x16x32_bf16 v[122:125], v[172:175], v[188:191], v[122:125]
	v_mfma_f32_16x16x32_bf16 v[114:117], v[180:183], v[188:191], v[114:117]
	v_mfma_f32_16x16x32_bf16 v[114:117], v[176:179], v[184:187], v[114:117]
	v_mfma_f32_16x16x32_bf16 v[98:101], v[176:179], v[206:209], v[98:101]
	v_mfma_f32_16x16x32_bf16 v[98:101], v[180:183], v[210:213], v[98:101]
	v_mfma_f32_16x16x32_bf16 v[106:109], v[172:175], v[210:213], v[106:109]
	v_mfma_f32_16x16x32_bf16 v[106:109], v[168:171], v[206:209], v[106:109]
	v_mfma_f32_16x16x32_bf16 v[90:93], v[168:171], v[214:217], v[90:93]
	v_mfma_f32_16x16x32_bf16 v[90:93], v[172:175], v[218:221], v[90:93]
	v_mfma_f32_16x16x32_bf16 v[82:85], v[180:183], v[218:221], v[82:85]
	v_mfma_f32_16x16x32_bf16 v[82:85], v[176:179], v[214:217], v[82:85]
	v_mfma_f32_16x16x32_bf16 v[66:69], v[176:179], v[222:225], v[66:69]
	v_mfma_f32_16x16x32_bf16 v[66:69], v[180:183], v[226:229], v[66:69]
	v_mfma_f32_16x16x32_bf16 v[74:77], v[172:175], v[226:229], v[74:77]
	v_mfma_f32_16x16x32_bf16 v[74:77], v[168:171], v[222:225], v[74:77]
	s_barrier
	s_add_i32 s22, s76, s29
	v_lshl_add_u64 v[230:231], s[40:41], 0, v[0:1]
	s_mov_b32 m0, s22
	ds_read_b128 v[184:187], v144 offset:16384
	ds_read_b128 v[188:191], v144 offset:17408
	ds_read_b128 v[206:209], v144 offset:18432
	ds_read_b128 v[210:213], v144 offset:19456
	ds_read_b128 v[214:217], v144 offset:20480
	ds_read_b128 v[218:221], v144 offset:21504
	ds_read_b128 v[222:225], v144 offset:22528
	ds_read_b128 v[226:229], v144 offset:23552
	global_load_lds_dwordx4 v[230:231], off
	s_add_i32 m0, s22, 0x2000
	s_add_u32 s22, s40, 0x40000
	v_lshl_add_u64 v[232:233], s[40:41], 0, v[130:131]
	s_addc_u32 s23, s41, 0
	s_add_i32 s58, s58, s29
	global_load_lds_dwordx4 v[232:233], off
	v_lshl_add_u64 v[234:235], s[22:23], 0, v[0:1]
	s_mov_b32 m0, s58
	s_nop 0
	global_load_lds_dwordx4 v[234:235], off
	v_lshl_add_u64 v[234:235], s[22:23], 0, v[130:131]
	s_add_i32 m0, s58, 0x2000
	s_nop 0
	global_load_lds_dwordx4 v[234:235], off
	v_lshl_add_u64 v[234:235], s[42:43], 0, v[134:135]
	s_mov_b32 m0, s45
	s_nop 0
	global_load_lds_dwordx4 v[234:235], off
	v_lshl_add_u64 v[234:235], s[42:43], 0, v[132:133]
	s_mov_b32 m0, s46
	s_nop 0
	global_load_lds_dwordx4 v[234:235], off
	s_waitcnt vmcnt(8)
	s_waitcnt lgkmcnt(0)
	s_barrier
; #define PG8_STAGE(bufoff, gbase, voff) do { _Pragma("unroll") for (int _i = 0; _i < 2; ++_i) \
;         __builtin_amdgcn_global_load_lds((const unsigned*)((const char*)(gbase) + (voff)[_i]), (PG8_LAS unsigned*)(lds + (bufoff) + ldsw + _i * 8192), 16, 0, 0); } while (0)
; #define PG8_LDA(dst, b, h) do { _Pragma("unroll") for (int m = 0; m < 4; ++m) _Pragma("unroll") for (int k = 0; k < 2; ++k) dst[m][k] = *(const PG8_LAS bf16x8*)(lds + PG8_SA(b, h) + aoff + m * 2048 + k * 1024); } while (0)
; #define PG8_LDB(dst, b, h) do { _Pragma("unroll") for (int n = 0; n < 2; ++n) _Pragma("unroll") for (int k = 0; k < 2; ++k) dst[n][k] = *(const PG8_LAS bf16x8*)(lds + PG8_SB(b, h) + boff + n * 2048 + k * 1024); } while (0)
; #define PG8_MMA(ai, bj, At, Bt) do { __builtin_amdgcn_s_setprio(1); _Pragma("unroll") for (int m = 0; m < 4; ++m) _Pragma("unroll") for (int n = 0; n < 2; ++n) _Pragma("unroll") for (int k = 0; k < 2; ++k) \
;         acc[ai][bj][m][n] = __builtin_amdgcn_mfma_f32_16x16x32_bf16(Bt[n][k], At[m][k], acc[ai][bj][m][n], 0, 0, 0); __builtin_amdgcn_s_setprio(0); } while (0)
; #define PG8_WAIT_V(n) asm volatile("s_waitcnt vmcnt(" #n ")" ::: "memory")
; #define PG8_WAIT_L(n) asm volatile("s_waitcnt lgkmcnt(" #n ")" ::: "memory")
; #define PG8_BAR __builtin_amdgcn_s_barrier()
; #define PG8_SCHED __builtin_amdgcn_sched_barrier(0)
; template <class Epi, class Sched, bool ALIGN_EPI = false, bool SP2 = false>
; __device__ __forceinline__ void gemm_phase(PG8_LAS unsigned char* lds, const Gemm g, const Sched& S, const Epi& E) {
;     ...
;             PG8_WAIT_V(8); PG8_WAIT_L(0); PG8_BAR; PG8_MMA(1, 0, At, B0); PG8_MMA(1, 1, At, B1); PG8_BAR; PG8_SCHED;
;             PG8_LDB(B0, 1, 0); PG8_LDB(B1, 1, 1); PG8_SCHED; PG8_LDA(At, 1, 0); PG8_STAGE(PG8_SA(0, 1), a2 + hstep, voffA);
;             PG8_WAIT_V(8); PG8_WAIT_L(0); PG8_BAR; PG8_MMA(0, 0, At, B0); PG8_MMA(0, 1, At, B1); PG8_BAR; PG8_SCHED;
	v_mfma_f32_16x16x32_bf16 v[62:65], v[146:149], v[184:187], v[62:65]
	v_mfma_f32_16x16x32_bf16 v[62:65], v[150:153], v[188:191], v[62:65]
	v_mfma_f32_16x16x32_bf16 v[54:57], v[164:167], v[188:191], v[54:57]
	v_mfma_f32_16x16x32_bf16 v[54:57], v[160:163], v[184:187], v[54:57]
	v_mfma_f32_16x16x32_bf16 v[38:41], v[160:163], v[206:209], v[38:41]
	v_mfma_f32_16x16x32_bf16 v[38:41], v[164:167], v[210:213], v[38:41]
	v_mfma_f32_16x16x32_bf16 v[46:49], v[150:153], v[210:213], v[46:49]
	v_mfma_f32_16x16x32_bf16 v[46:49], v[146:149], v[206:209], v[46:49]
	v_mfma_f32_16x16x32_bf16 v[30:33], v[146:149], v[214:217], v[30:33]
	v_mfma_f32_16x16x32_bf16 v[30:33], v[150:153], v[218:221], v[30:33]
	v_mfma_f32_16x16x32_bf16 v[22:25], v[164:167], v[218:221], v[22:25]
	v_mfma_f32_16x16x32_bf16 v[22:25], v[160:163], v[214:217], v[22:25]
	v_mfma_f32_16x16x32_bf16 v[6:9], v[160:163], v[222:225], v[6:9]
	v_mfma_f32_16x16x32_bf16 v[6:9], v[164:167], v[226:229], v[6:9]
	v_mfma_f32_16x16x32_bf16 v[14:17], v[150:153], v[226:229], v[14:17]
	v_mfma_f32_16x16x32_bf16 v[14:17], v[146:149], v[222:225], v[14:17]
	v_mfma_f32_16x16x32_bf16 v[58:61], v[168:171], v[184:187], v[58:61]
	v_mfma_f32_16x16x32_bf16 v[58:61], v[172:175], v[188:191], v[58:61]
	v_mfma_f32_16x16x32_bf16 v[50:53], v[180:183], v[188:191], v[50:53]
	v_mfma_f32_16x16x32_bf16 v[50:53], v[176:179], v[184:187], v[50:53]
	v_mfma_f32_16x16x32_bf16 v[34:37], v[176:179], v[206:209], v[34:37]
	v_mfma_f32_16x16x32_bf16 v[34:37], v[180:183], v[210:213], v[34:37]
	v_mfma_f32_16x16x32_bf16 v[42:45], v[172:175], v[210:213], v[42:45]
	v_mfma_f32_16x16x32_bf16 v[42:45], v[168:171], v[206:209], v[42:45]
	v_mfma_f32_16x16x32_bf16 v[26:29], v[168:171], v[214:217], v[26:29]
	v_mfma_f32_16x16x32_bf16 v[26:29], v[172:175], v[218:221], v[26:29]
	v_mfma_f32_16x16x32_bf16 v[18:21], v[180:183], v[218:221], v[18:21]
	v_mfma_f32_16x16x32_bf16 v[18:21], v[176:179], v[214:217], v[18:21]
	v_mfma_f32_16x16x32_bf16 v[2:5], v[176:179], v[222:225], v[2:5]
	v_mfma_f32_16x16x32_bf16 v[2:5], v[180:183], v[226:229], v[2:5]
	v_mfma_f32_16x16x32_bf16 v[10:13], v[172:175], v[226:229], v[10:13]
	v_mfma_f32_16x16x32_bf16 v[10:13], v[168:171], v[222:225], v[10:13]
	s_barrier
	s_add_i32 s58, 0, 0x18000
	v_add_u32_e32 v145, s58, v142
	s_add_i32 s59, 0, 0x1c000
	ds_read_b128 v[146:149], v145
	ds_read_b128 v[150:153], v145 offset:1024
	ds_read_b128 v[160:163], v145 offset:2048
	ds_read_b128 v[164:167], v145 offset:3072
	v_add_u32_e32 v145, s59, v142
	ds_read_b128 v[168:171], v145
	ds_read_b128 v[172:175], v145 offset:1024
	ds_read_b128 v[176:179], v145 offset:2048
	ds_read_b128 v[180:183], v145 offset:3072
	s_add_u32 s22, s42, 0x40000
	s_addc_u32 s23, s43, 0
	s_mov_b32 m0, s47
	v_lshl_add_u64 v[234:235], s[22:23], 0, v[134:135]
	ds_read_b128 v[184:187], v144 offset:32768
	ds_read_b128 v[188:191], v144 offset:33792
	ds_read_b128 v[206:209], v144 offset:34816
	ds_read_b128 v[210:213], v144 offset:35840
	ds_read_b128 v[214:217], v144 offset:36864
	ds_read_b128 v[218:221], v144 offset:37888
	ds_read_b128 v[222:225], v144 offset:38912
	ds_read_b128 v[226:229], v144 offset:39936
	global_load_lds_dwordx4 v[234:235], off
	v_lshl_add_u64 v[234:235], s[22:23], 0, v[132:133]
	s_mov_b32 m0, s48
	s_nop 0
	global_load_lds_dwordx4 v[234:235], off
	s_waitcnt vmcnt(8)
	s_waitcnt lgkmcnt(0)
	s_barrier
	v_mfma_f32_16x16x32_bf16 v[126:129], v[146:149], v[184:187], v[126:129]
	v_mfma_f32_16x16x32_bf16 v[126:129], v[150:153], v[188:191], v[126:129]
	v_mfma_f32_16x16x32_bf16 v[118:121], v[164:167], v[188:191], v[118:121]
	v_mfma_f32_16x16x32_bf16 v[118:121], v[160:163], v[184:187], v[118:121]
	v_mfma_f32_16x16x32_bf16 v[102:105], v[160:163], v[206:209], v[102:105]
	v_mfma_f32_16x16x32_bf16 v[102:105], v[164:167], v[210:213], v[102:105]
	v_mfma_f32_16x16x32_bf16 v[110:113], v[150:153], v[210:213], v[110:113]
	v_mfma_f32_16x16x32_bf16 v[110:113], v[146:149], v[206:209], v[110:113]
	v_mfma_f32_16x16x32_bf16 v[94:97], v[146:149], v[214:217], v[94:97]
	v_mfma_f32_16x16x32_bf16 v[94:97], v[150:153], v[218:221], v[94:97]
	v_mfma_f32_16x16x32_bf16 v[86:89], v[164:167], v[218:221], v[86:89]
	v_mfma_f32_16x16x32_bf16 v[86:89], v[160:163], v[214:217], v[86:89]
	v_mfma_f32_16x16x32_bf16 v[70:73], v[160:163], v[222:225], v[70:73]
	v_mfma_f32_16x16x32_bf16 v[70:73], v[164:167], v[226:229], v[70:73]
	v_mfma_f32_16x16x32_bf16 v[78:81], v[150:153], v[226:229], v[78:81]
	v_mfma_f32_16x16x32_bf16 v[78:81], v[146:149], v[222:225], v[78:81]
	v_mfma_f32_16x16x32_bf16 v[122:125], v[168:171], v[184:187], v[122:125]
	v_mfma_f32_16x16x32_bf16 v[122:125], v[172:175], v[188:191], v[122:125]
	v_mfma_f32_16x16x32_bf16 v[114:117], v[180:183], v[188:191], v[114:117]
	v_mfma_f32_16x16x32_bf16 v[114:117], v[176:179], v[184:187], v[114:117]
	v_mfma_f32_16x16x32_bf16 v[98:101], v[176:179], v[206:209], v[98:101]
	v_mfma_f32_16x16x32_bf16 v[98:101], v[180:183], v[210:213], v[98:101]
	v_mfma_f32_16x16x32_bf16 v[106:109], v[172:175], v[210:213], v[106:109]
	v_mfma_f32_16x16x32_bf16 v[106:109], v[168:171], v[206:209], v[106:109]
	v_mfma_f32_16x16x32_bf16 v[90:93], v[168:171], v[214:217], v[90:93]
	v_mfma_f32_16x16x32_bf16 v[90:93], v[172:175], v[218:221], v[90:93]
	v_mfma_f32_16x16x32_bf16 v[82:85], v[180:183], v[218:221], v[82:85]
	v_mfma_f32_16x16x32_bf16 v[82:85], v[176:179], v[214:217], v[82:85]
	v_mfma_f32_16x16x32_bf16 v[66:69], v[176:179], v[222:225], v[66:69]
	v_mfma_f32_16x16x32_bf16 v[66:69], v[180:183], v[226:229], v[66:69]
	v_mfma_f32_16x16x32_bf16 v[74:77], v[172:175], v[226:229], v[74:77]
	v_mfma_f32_16x16x32_bf16 v[74:77], v[168:171], v[222:225], v[74:77]
	s_barrier
; #define PG8_STAGE(bufoff, gbase, voff) do { _Pragma("unroll") for (int _i = 0; _i < 2; ++_i) \
;         __builtin_amdgcn_global_load_lds((const unsigned*)((const char*)(gbase) + (voff)[_i]), (PG8_LAS unsigned*)(lds + (bufoff) + ldsw + _i * 8192), 16, 0, 0); } while (0)
; #define PG8_LDA(dst, b, h) do { _Pragma("unroll") for (int m = 0; m < 4; ++m) _Pragma("unroll") for (int k = 0; k < 2; ++k) dst[m][k] = *(const PG8_LAS bf16x8*)(lds + PG8_SA(b, h) + aoff + m * 2048 + k * 1024); } while (0)
; #define PG8_MMA(ai, bj, At, Bt) do { __builtin_amdgcn_s_setprio(1); _Pragma("unroll") for (int m = 0; m < 4; ++m) _Pragma("unroll") for (int n = 0; n < 2; ++n) _Pragma("unroll") for (int k = 0; k < 2; ++k) \
;         acc[ai][bj][m][n] = __builtin_amdgcn_mfma_f32_16x16x32_bf16(Bt[n][k], At[m][k], acc[ai][bj][m][n], 0, 0, 0); __builtin_amdgcn_s_setprio(0); } while (0)
; #define PG8_WAIT_V(n) asm volatile("s_waitcnt vmcnt(" #n ")" ::: "memory")
; #define PG8_WAIT_L(n) asm volatile("s_waitcnt lgkmcnt(" #n ")" ::: "memory")
; #define PG8_BAR __builtin_amdgcn_s_barrier()
; #define PG8_SCHED __builtin_amdgcn_sched_barrier(0)
; template <class Epi, class Sched, bool ALIGN_EPI = false, bool SP2 = false>
; __device__ __forceinline__ void gemm_phase(PG8_LAS unsigned char* lds, const Gemm g, const Sched& S, const Epi& E) {
;     ...
;             PG8_LDA(At, 1, 1); PG8_STAGE(PG8_SB(1, 0), b3, voffB); PG8_STAGE(PG8_SB(1, 1), b3 + hstep, voffB); PG8_STAGE(PG8_SA(1, 0), a3, voffA);
;             PG8_WAIT_V(8); PG8_WAIT_L(0); PG8_BAR; PG8_MMA(1, 0, At, B0); PG8_MMA(1, 1, At, B1); PG8_BAR; PG8_SCHED;
;     ...
;         if constexpr (ALIGN_EPI) { if (wr == 0) PG8_BAR; }
	s_add_i32 s22, s58, s29
	v_lshl_add_u64 v[230:231], v[230:231], 0, s[38:39]
	s_mov_b32 m0, s22
	ds_read_b128 v[184:187], v144 offset:49152
	ds_read_b128 v[188:191], v144 offset:50176
	ds_read_b128 v[206:209], v144 offset:51200
	ds_read_b128 v[210:213], v144 offset:52224
	ds_read_b128 v[214:217], v144 offset:53248
	ds_read_b128 v[218:221], v144 offset:54272
	ds_read_b128 v[222:225], v144 offset:55296
	ds_read_b128 v[226:229], v144 offset:56320
	global_load_lds_dwordx4 v[230:231], off
	s_add_i32 m0, s22, 0x2000
	s_add_u32 s22, s40, 0x40080
	v_lshl_add_u64 v[230:231], v[232:233], 0, s[38:39]
	s_addc_u32 s23, s41, 0
	s_add_i32 s40, s59, s29
	global_load_lds_dwordx4 v[230:231], off
	v_lshl_add_u64 v[230:231], s[22:23], 0, v[0:1]
	s_mov_b32 m0, s40
	s_nop 0
	global_load_lds_dwordx4 v[230:231], off
	v_lshl_add_u64 v[230:231], s[22:23], 0, v[130:131]
	s_add_i32 m0, s40, 0x2000
	s_nop 0
	global_load_lds_dwordx4 v[230:231], off
	v_lshl_add_u64 v[230:231], s[26:27], 0, v[134:135]
	s_mov_b32 m0, s49
	s_nop 0
	global_load_lds_dwordx4 v[230:231], off
	v_lshl_add_u64 v[230:231], s[26:27], 0, v[132:133]
	s_mov_b32 m0, s50
	s_nop 0
	global_load_lds_dwordx4 v[230:231], off
	s_waitcnt vmcnt(8)
	s_waitcnt lgkmcnt(0)
	s_barrier
	v_mfma_f32_16x16x32_bf16 v[62:65], v[146:149], v[184:187], v[62:65]
	v_mfma_f32_16x16x32_bf16 v[62:65], v[150:153], v[188:191], v[62:65]
	v_mfma_f32_16x16x32_bf16 v[54:57], v[164:167], v[188:191], v[54:57]
	v_mfma_f32_16x16x32_bf16 v[54:57], v[160:163], v[184:187], v[54:57]
	v_mfma_f32_16x16x32_bf16 v[38:41], v[160:163], v[206:209], v[38:41]
	v_mfma_f32_16x16x32_bf16 v[38:41], v[164:167], v[210:213], v[38:41]
	v_mfma_f32_16x16x32_bf16 v[46:49], v[150:153], v[210:213], v[46:49]
	v_mfma_f32_16x16x32_bf16 v[46:49], v[146:149], v[206:209], v[46:49]
	v_mfma_f32_16x16x32_bf16 v[30:33], v[146:149], v[214:217], v[30:33]
	v_mfma_f32_16x16x32_bf16 v[30:33], v[150:153], v[218:221], v[30:33]
	v_mfma_f32_16x16x32_bf16 v[22:25], v[164:167], v[218:221], v[22:25]
	v_mfma_f32_16x16x32_bf16 v[22:25], v[160:163], v[214:217], v[22:25]
	v_mfma_f32_16x16x32_bf16 v[6:9], v[160:163], v[222:225], v[6:9]
	v_mfma_f32_16x16x32_bf16 v[6:9], v[164:167], v[226:229], v[6:9]
	v_mfma_f32_16x16x32_bf16 v[14:17], v[150:153], v[226:229], v[14:17]
	v_mfma_f32_16x16x32_bf16 v[14:17], v[146:149], v[222:225], v[14:17]
	v_mfma_f32_16x16x32_bf16 v[58:61], v[168:171], v[184:187], v[58:61]
	v_mfma_f32_16x16x32_bf16 v[58:61], v[172:175], v[188:191], v[58:61]
	v_mfma_f32_16x16x32_bf16 v[50:53], v[180:183], v[188:191], v[50:53]
	v_mfma_f32_16x16x32_bf16 v[50:53], v[176:179], v[184:187], v[50:53]
	v_mfma_f32_16x16x32_bf16 v[34:37], v[176:179], v[206:209], v[34:37]
	v_mfma_f32_16x16x32_bf16 v[34:37], v[180:183], v[210:213], v[34:37]
	v_mfma_f32_16x16x32_bf16 v[42:45], v[172:175], v[210:213], v[42:45]
	v_mfma_f32_16x16x32_bf16 v[42:45], v[168:171], v[206:209], v[42:45]
	v_mfma_f32_16x16x32_bf16 v[26:29], v[168:171], v[214:217], v[26:29]
	v_mfma_f32_16x16x32_bf16 v[26:29], v[172:175], v[218:221], v[26:29]
	v_mfma_f32_16x16x32_bf16 v[18:21], v[180:183], v[218:221], v[18:21]
	v_mfma_f32_16x16x32_bf16 v[18:21], v[176:179], v[214:217], v[18:21]
	v_mfma_f32_16x16x32_bf16 v[2:5], v[176:179], v[222:225], v[2:5]
	v_mfma_f32_16x16x32_bf16 v[2:5], v[180:183], v[226:229], v[2:5]
	v_mfma_f32_16x16x32_bf16 v[10:13], v[172:175], v[226:229], v[10:13]
	v_mfma_f32_16x16x32_bf16 v[10:13], v[168:171], v[222:225], v[10:13]
	s_barrier
	s_add_i32 s57, s57, 2
	s_add_u32 s55, s55, 0x100
	s_addc_u32 s56, s56, 0
	s_cmp_gt_u32 s57, 13
	s_mov_b64 s[22:23], s[24:25]
	s_cbranch_scc0 .LBB0_409
	s_and_b64 vcc, exec, s[6:7]
	s_cbranch_vccz .LBB0_412
	s_barrier
